# phase 4 tile header: removed the vmcnt(0) store drain as in the other GEMM tile headers
# baseline (speedup 1.0000x reference)
.LBB0_122:
	s_and_b32 s8, s2, 15
	s_lshl_b32 s2, s2, 3
	s_or_b32 s5, s8, s50
	s_and_b32 s4, s2, 0x380
	v_readlane_b32 s16, v250, 53
	s_lshl_b32 s14, s5, 18
	s_add_i32 s15, s4, 0x1480
	s_lshl_b32 s2, s5, 19
	v_readlane_b32 s18, v250, 55
	v_readlane_b32 s17, v250, 54
	v_readlane_b32 s19, v250, 56
	s_add_u32 s16, s18, s2
	v_readlane_b32 s22, v250, 59
	s_addc_u32 s17, s19, 0
	v_readlane_b32 s23, v250, 60
	s_add_u32 s6, s22, s14
	s_addc_u32 s7, s23, 0
	s_add_i32 s2, s50, s8
	s_lshl_b32 s2, s2, 19
	v_readlane_b32 s20, v250, 57
	s_add_u32 s18, s18, s2
	s_mov_b32 s5, s3
	s_addc_u32 s19, s19, 0
	v_mov_b32_e32 v172, 0
	v_mov_b32_e32 v175, 0
	v_mov_b32_e32 v178, 0
	v_mov_b32_e32 v176, 0
	v_mov_b32_e32 v174, 0
	v_mov_b32_e32 v180, 0
	v_mov_b32_e32 v179, 0
	v_mov_b32_e32 v177, 0
	v_mov_b32_e32 v173, 0
	v_mov_b32_e32 v169, 0
	v_mov_b32_e32 v171, 0
	v_mov_b32_e32 v170, 0
	v_mov_b32_e32 v168, 0
	v_mov_b32_e32 v167, 0
	v_mov_b32_e32 v166, 0
	v_mov_b32_e32 v165, 0
	v_mov_b32_e32 v164, 0
	v_mov_b32_e32 v161, 0
	v_mov_b32_e32 v163, 0
	v_mov_b32_e32 v162, 0
	v_mov_b32_e32 v160, 0
	v_mov_b32_e32 v159, 0
	v_mov_b32_e32 v158, 0
	v_mov_b32_e32 v157, 0
	v_mov_b32_e32 v156, 0
	v_mov_b32_e32 v153, 0
	v_mov_b32_e32 v155, 0
	v_mov_b32_e32 v154, 0
	v_mov_b32_e32 v152, 0
	s_nop 0
	v_mov_b32_e32 v151, 0
	v_mov_b32_e32 v150, 0
	v_mov_b32_e32 v149, 0
	v_mov_b32_e32 v148, 0
	s_mov_b32 s20, 0
	v_readlane_b32 s21, v250, 58
	v_readlane_b32 s24, v250, 61
	v_readlane_b32 s25, v250, 62
	v_readlane_b32 s26, v250, 63
	v_readlane_b32 s27, v249, 0
	v_readlane_b32 s28, v249, 1
	v_readlane_b32 s29, v249, 2
	v_readlane_b32 s30, v249, 3
	v_readlane_b32 s31, v249, 4
